# adds phase-4 tail rebalancing: the 40 leftover branch-projection items run on workgroups 40-79 in parallel with the leftover gate items, gate tiles handed over by release fence, flag and acquire
# speedup vs baseline: 1.0097x; 1.0054x over previous
.LBB0_770:
	s_nop 0
	v_add_u32_e32 v22, s8, v151
	ds_read_b128 v[18:21], v22
	ds_read_b128 v[22:25], v22 offset:32768
	v_ashrrev_i32_e32 v17, 31, v16
	v_lshlrev_b64 v[26:27], 10, v[16:17]
	v_lshl_add_u64 v[26:27], v[26:27], 0, v[108:109]
	s_waitcnt lgkmcnt(1)
	v_cvt_f32_f16_e32 v30, v18
	v_cvt_f32_f16_sdwa v31, v18 dst_sel:DWORD dst_unused:UNUSED_PAD src0_sel:WORD_1
	v_cvt_f32_f16_e32 v18, v19
	v_cvt_f32_f16_sdwa v19, v19 dst_sel:DWORD dst_unused:UNUSED_PAD src0_sel:WORD_1
	v_cvt_f32_f16_e32 v32, v20
	v_cvt_f32_f16_sdwa v33, v20 dst_sel:DWORD dst_unused:UNUSED_PAD src0_sel:WORD_1
	v_cvt_f32_f16_e32 v20, v21
	v_cvt_f32_f16_sdwa v21, v21 dst_sel:DWORD dst_unused:UNUSED_PAD src0_sel:WORD_1
	s_waitcnt lgkmcnt(0)
	v_cvt_f32_f16_e32 v34, v22
	v_cvt_f32_f16_sdwa v35, v22 dst_sel:DWORD dst_unused:UNUSED_PAD src0_sel:WORD_1
	v_cvt_f32_f16_e32 v22, v23
	v_cvt_f32_f16_sdwa v23, v23 dst_sel:DWORD dst_unused:UNUSED_PAD src0_sel:WORD_1
	v_cvt_f32_f16_e32 v36, v24
	v_cvt_f32_f16_sdwa v37, v24 dst_sel:DWORD dst_unused:UNUSED_PAD src0_sel:WORD_1
	v_cvt_f32_f16_e32 v24, v25
	v_cvt_f32_f16_sdwa v25, v25 dst_sel:DWORD dst_unused:UNUSED_PAD src0_sel:WORD_1
	v_pk_add_f32 v[18:19], v[6:7], v[18:19]
	v_pk_add_f32 v[30:31], v[4:5], v[30:31]
	v_pk_add_f32 v[20:21], v[2:3], v[20:21]
	v_pk_add_f32 v[32:33], v[0:1], v[32:33]
	v_pk_add_f32 v[22:23], v[14:15], v[22:23]
	v_pk_add_f32 v[34:35], v[12:13], v[34:35]
	v_pk_add_f32 v[24:25], v[10:11], v[24:25]
	v_pk_add_f32 v[36:37], v[8:9], v[36:37]
	v_mul_f32_e32 v17, 0xbfb8aa3b, v30
	v_mul_f32_e32 v30, 0xbfb8aa3b, v31
	v_mul_f32_e32 v18, 0xbfb8aa3b, v18
	v_mul_f32_e32 v19, 0xbfb8aa3b, v19
	v_mul_f32_e32 v31, 0xbfb8aa3b, v32
	v_mul_f32_e32 v32, 0xbfb8aa3b, v33
	v_mul_f32_e32 v20, 0xbfb8aa3b, v20
	v_mul_f32_e32 v21, 0xbfb8aa3b, v21
	v_mul_f32_e32 v33, 0xbfb8aa3b, v34
	v_mul_f32_e32 v34, 0xbfb8aa3b, v35
	v_mul_f32_e32 v22, 0xbfb8aa3b, v22
	v_mul_f32_e32 v23, 0xbfb8aa3b, v23
	v_mul_f32_e32 v35, 0xbfb8aa3b, v36
	v_mul_f32_e32 v36, 0xbfb8aa3b, v37
	v_mul_f32_e32 v24, 0xbfb8aa3b, v24
	v_mul_f32_e32 v25, 0xbfb8aa3b, v25
	v_exp_f32_e32 v17, v17
	v_exp_f32_e32 v30, v30
	v_exp_f32_e32 v18, v18
	v_exp_f32_e32 v19, v19
	v_exp_f32_e32 v31, v31
	v_exp_f32_e32 v32, v32
	v_exp_f32_e32 v20, v20
	v_exp_f32_e32 v21, v21
	v_exp_f32_e32 v33, v33
	v_exp_f32_e32 v34, v34
	v_exp_f32_e32 v22, v22
	v_exp_f32_e32 v23, v23
	v_exp_f32_e32 v35, v35
	v_exp_f32_e32 v36, v36
	v_exp_f32_e32 v24, v24
	v_exp_f32_e32 v25, v25
	v_add_f32_e32 v17, 1.0, v17
	v_add_f32_e32 v30, 1.0, v30
	v_add_f32_e32 v18, 1.0, v18
	v_add_f32_e32 v19, 1.0, v19
	v_add_f32_e32 v31, 1.0, v31
	v_add_f32_e32 v32, 1.0, v32
	v_add_f32_e32 v20, 1.0, v20
	v_add_f32_e32 v21, 1.0, v21
	v_add_f32_e32 v33, 1.0, v33
	v_add_f32_e32 v34, 1.0, v34
	v_add_f32_e32 v22, 1.0, v22
	v_add_f32_e32 v23, 1.0, v23
	v_add_f32_e32 v35, 1.0, v35
	v_add_f32_e32 v36, 1.0, v36
	v_add_f32_e32 v24, 1.0, v24
	v_add_f32_e32 v25, 1.0, v25
	v_rcp_f32_e32 v17, v17
	v_rcp_f32_e32 v30, v30
	v_rcp_f32_e32 v18, v18
	v_rcp_f32_e32 v19, v19
	v_rcp_f32_e32 v31, v31
	v_rcp_f32_e32 v32, v32
	v_rcp_f32_e32 v20, v20
	v_rcp_f32_e32 v21, v21
	v_rcp_f32_e32 v33, v33
	v_rcp_f32_e32 v34, v34
	v_rcp_f32_e32 v22, v22
	v_rcp_f32_e32 v23, v23
	v_rcp_f32_e32 v35, v35
	v_rcp_f32_e32 v36, v36
	v_rcp_f32_e32 v24, v24
	v_rcp_f32_e32 v25, v25
	s_addk_i32 s8, 0x1000
	v_lshlrev_b64 v[26:27], 1, v[26:27]
	v_add_u32_e32 v16, 16, v16
	s_cmpk_eq_u32 s8, 0x8000
	v_lshl_add_u64 v[28:29], s[60:61], 0, v[26:27]
	v_cvt_pk_f16_f32 v21, v20, v21
	v_cvt_pk_f16_f32 v20, v31, v32
	v_cvt_pk_f16_f32 v19, v18, v19
	v_cvt_pk_f16_f32 v18, v17, v30
	v_lshl_add_u64 v[26:27], s[0:1], 0, v[26:27]
	v_cvt_pk_f16_f32 v25, v24, v25
	v_cvt_pk_f16_f32 v24, v35, v36
	v_cvt_pk_f16_f32 v23, v22, v23
	v_cvt_pk_f16_f32 v22, v33, v34
	global_store_dwordx4 v[28:29], v[18:21], off
	global_store_dwordx4 v[26:27], v[22:25], off
	s_cbranch_scc0 .LBB0_770
	s_add_i32 s11, s11, s84
	v_add_u32_e32 v186, s3, v186
	v_add_u32_e32 v187, s3, v187
	s_cmpk_gt_i32 s11, 0x427
	v_add_u32_e32 v197, s3, v197
	s_barrier
	s_cbranch_scc0 .LBB0_767
	v_lshrrev_b32_e32 v1, 3, v152
	v_or_b32_e32 v106, v169, v1
	v_or_b32_e32 v111, 24, v106
	v_lshrrev_b32_e32 v3, 1, v111
	v_lshrrev_b32_e32 v0, 1, v106
	v_or_b32_e32 v108, 8, v106
	v_xor_b32_e32 v3, v3, v153
	v_xor_b32_e32 v0, v0, v153
	v_lshrrev_b32_e32 v2, 1, v108
	v_lshlrev_b32_e32 v3, 3, v3
	v_lshlrev_b32_e32 v0, 3, v0
	v_xor_b32_e32 v2, v2, v153
	v_and_b32_e32 v112, 56, v3
	v_lshrrev_b32_e32 v3, 4, v152
	v_and_b32_e32 v107, 56, v0
	v_lshlrev_b32_e32 v2, 3, v2
	v_bitop3_b32 v5, v3, v162, 7 bitop3:0x78
	v_bitop3_b32 v3, v3, v129, 4 bitop3:0x36
	v_add3_u32 v120, v1, s10, v169
	v_lshl_add_u32 v1, v1, 10, v178
	v_and_b32_e32 v109, 56, v2
	v_mov_b32_e32 v65, 0
	v_lshlrev_b32_e32 v117, 4, v3
	v_lshlrev_b32_e32 v3, 1, v170
	v_add_lshl_u32 v64, v1, v107, 1
	v_lshlrev_b32_e32 v114, 4, v5
	v_lshl_or_b32 v118, v172, 8, v3
	v_lshl_add_u32 v119, v173, 1, v3
	s_mov_b64 s[6:7], 0x80
	v_lshl_add_u64 v[8:9], s[30:31], 0, v[64:65]
	v_add_u32_e32 v3, v1, v109
	v_mov_b32_e32 v5, 0x4000
	v_lshl_add_u64 v[66:67], v[8:9], 0, s[6:7]
	v_lshl_add_u32 v8, v3, 1, v5
	v_mov_b32_e32 v9, v65
	v_lshl_add_u64 v[8:9], s[30:31], 0, v[8:9]
	v_add_u32_e32 v64, 0x8000, v64
	v_add_u32_e32 v1, v1, v112
	v_mov_b32_e32 v3, 0xc000
	v_or_b32_e32 v110, 16, v106
	v_lshl_add_u64 v[68:69], v[8:9], 0, s[6:7]
	v_lshl_add_u64 v[8:9], s[30:31], 0, v[64:65]
	v_lshl_add_u32 v64, v1, 1, v3
	v_lshl_or_b32 v0, v106, 10, v107
	v_lshl_or_b32 v2, v108, 10, v109
	v_lshl_or_b32 v4, v110, 10, v107
	v_lshl_or_b32 v6, v111, 10, v112
	v_lshl_or_b32 v113, v154, 12, v174
	s_add_u32 s4, s30, 0x80
	v_lshl_add_u64 v[70:71], v[8:9], 0, s[6:7]
	v_lshl_add_u64 v[8:9], s[30:31], 0, v[64:65]
	v_lshlrev_b32_e32 v115, 7, v171
	v_lshlrev_b32_e32 v116, 7, v170
	s_addc_u32 s5, s31, 0
	v_add_u32_e32 v121, 8, v120
	v_add_u32_e32 v122, 16, v120
	v_add_u32_e32 v123, 24, v120
	v_lshl_add_u64 v[72:73], v[8:9], 0, s[6:7]
	v_mov_b32_e32 v124, 0x427f
	v_lshlrev_b32_e32 v125, 1, v107
	v_lshlrev_b32_e32 v126, 1, v109
	v_lshlrev_b32_e32 v127, 1, v112
	s_mov_b32 s10, 0xce20000
	s_mov_b32 s11, 0x10c0000
	v_lshlrev_b32_e32 v129, 1, v0
	v_add_u32_e32 v130, 0x4000, v113
	v_add_u32_e32 v131, 0x400, v113
	v_lshlrev_b32_e32 v132, 1, v2
	v_add_u32_e32 v133, 0x4400, v113
	v_add_u32_e32 v134, 0x800, v113
	v_lshlrev_b32_e32 v135, 1, v4
	v_add_u32_e32 v136, 0x4800, v113
	v_add_u32_e32 v137, 0xc00, v113
	v_lshlrev_b32_e32 v138, 1, v6
	v_add_u32_e32 v139, 0x4c00, v113
	s_mov_b32 s20, s2
	s_cmp_eq_u32 s84, 0x200
	s_cbranch_scc0 .Lp5_nosig
	s_cmp_lt_u32 s2, 40
	s_cbranch_scc0 .Lp5_nosig
	s_waitcnt vmcnt(0) lgkmcnt(0)
	s_barrier
	s_and_saveexec_b64 s[6:7], s[82:83]
	s_cbranch_execz .Lp5_sigdone
	buffer_wbl2 sc1
	s_waitcnt vmcnt(0)
	s_add_u32 s8, s30, 0xf9c4000
	s_addc_u32 s9, s31, 0
	s_lshl_b32 s12, s2, 2
	v_mov_b32_e32 v0, s12
	v_mov_b32_e32 v1, 1
	global_store_dword v0, v1, s[8:9] sc0 sc1
	s_waitcnt vmcnt(0)

.Lp5_nosig:
.LBB0_773:
	s_mul_hi_i32 s6, s20, 0xf6603d99
	s_add_i32 s6, s6, s20
	s_lshr_b32 s7, s6, 31
	s_ashr_i32 s6, s6, 7
	s_add_i32 s24, s6, s7
	s_mul_i32 s6, s24, 0xffffff7b
	s_add_i32 s6, s6, s20
	s_lshl_b32 s12, s6, 7
	v_add_u32_e32 v1, s12, v108
	v_med3_i32 v1, v1, 0, v124
	v_lshl_or_b32 v2, v1, 10, v109
	v_add_u32_e32 v1, s12, v110
	v_med3_i32 v1, v1, 0, v124
	v_lshl_or_b32 v4, v1, 10, v107
	v_add_u32_e32 v1, s12, v111
	s_lshl_b32 s6, s24, 7
	v_med3_i32 v1, v1, 0, v124
	s_mulk_i32 s24, 0x4280
	v_lshl_or_b32 v6, v1, 10, v112
	v_subrev_u32_e32 v1, s24, v120
	v_med3_i32 v1, v1, 0, v124
	v_lshl_or_b32 v64, v1, 11, v125
	v_subrev_u32_e32 v1, s24, v121
	v_med3_i32 v1, v1, 0, v124
	v_lshl_add_u64 v[74:75], s[4:5], 0, v[64:65]
	v_lshl_or_b32 v64, v1, 11, v126
	v_subrev_u32_e32 v1, s24, v122
	v_med3_i32 v1, v1, 0, v124
	s_ashr_i32 s7, s6, 31
	v_add_u32_e32 v0, s12, v106
	v_lshl_add_u64 v[76:77], s[4:5], 0, v[64:65]
	v_lshl_or_b32 v64, v1, 11, v125
	v_subrev_u32_e32 v1, s24, v123
	s_lshl_b64 s[8:9], s[6:7], 11
	v_med3_i32 v0, v0, 0, v124
	v_med3_i32 v1, v1, 0, v124
	s_add_u32 s7, s30, s8
	v_lshl_or_b32 v0, v0, 10, v107
	v_lshl_add_u64 v[78:79], s[4:5], 0, v[64:65]
	v_lshl_or_b32 v64, v1, 11, v127
	s_addc_u32 s21, s31, s9
	v_lshl_add_u64 v[80:81], s[4:5], 0, v[64:65]
	v_lshl_add_u64 v[82:83], v[66:67], 0, s[8:9]
	v_lshl_add_u64 v[84:85], v[68:69], 0, s[8:9]
	v_lshl_add_u64 v[86:87], v[70:71], 0, s[8:9]
	v_lshl_add_u64 v[88:89], v[72:73], 0, s[8:9]
	v_lshlrev_b32_e32 v64, 1, v0
	v_lshlrev_b32_e32 v193, 1, v2
	v_lshlrev_b32_e32 v194, 1, v4
	v_lshlrev_b32_e32 v195, 1, v6
	s_mov_b64 s[16:17], -1
	s_branch .LBB0_775

.LBB0_781:
	v_or_b32_e32 v0, s6, v128
	v_ashrrev_i32_e32 v1, 31, v0
	v_subrev_u32_e32 v2, s24, v168
	s_mov_b32 s6, 0
	s_waitcnt lgkmcnt(0)
	s_barrier
	s_cmp_eq_u32 s84, 0x200
	s_cbranch_scc0 .Lp5_nowait
	s_cmpk_lt_i32 s20, 0x400
	s_cbranch_scc1 .Lp5_nowait
	s_sub_i32 s7, s20, 0x400
	s_lshl_b32 s7, s7, 2
	s_add_u32 s8, s30, 0xf9c4000
	s_addc_u32 s9, s31, 0
	s_and_saveexec_b64 s[12:13], s[82:83]
	s_cbranch_execz .Lp5_got
	v_mov_b32_e32 v3, s7
.Lp5_spin:
	global_load_dword v4, v3, s[8:9] sc1
	s_waitcnt vmcnt(0)
	v_readfirstlane_b32 s7, v4
	s_nop 3
	s_cmp_lg_u32 s7, 0
	s_cbranch_scc1 .Lp5_acq
	s_sleep 4
	s_branch .Lp5_spin
.Lp5_acq:
	buffer_inv sc1
	s_waitcnt vmcnt(0)
.Lp5_got:
	s_or_b64 exec, exec, s[12:13]
	s_barrier
.Lp5_nowait:
.LBB0_782:
	v_ashrrev_i32_e32 v3, 31, v2
	v_lshlrev_b64 v[4:5], 10, v[2:3]
	v_lshl_add_u64 v[4:5], v[4:5], 0, v[0:1]
	v_lshlrev_b64 v[4:5], 1, v[4:5]
	v_lshl_add_u64 v[12:13], s[0:1], 0, v[4:5]
	v_lshl_add_u64 v[20:21], s[60:61], 0, v[4:5]
	global_load_dwordx4 v[4:7], v[12:13], off
	global_load_dwordx4 v[8:11], v[20:21], off
	v_add_u32_e32 v3, s6, v151
	ds_read_b128 v[12:15], v3 offset:32768
	ds_read_b128 v[16:19], v3
	s_addk_i32 s6, 0x1000
	v_add_u32_e32 v2, 16, v2
	s_cmpk_eq_u32 s6, 0x8000
	s_waitcnt vmcnt(1) lgkmcnt(1)
	v_pk_mul_f16 v3, v12, v4
	v_pk_mul_f16 v4, v13, v5
	v_pk_mul_f16 v5, v14, v6
	v_pk_mul_f16 v6, v15, v7
	s_waitcnt vmcnt(0) lgkmcnt(0)
	v_pk_fma_f16 v7, v19, v11, v6
	v_pk_fma_f16 v6, v18, v10, v5
	v_pk_fma_f16 v5, v17, v9, v4
	v_pk_fma_f16 v4, v16, v8, v3
	global_store_dwordx4 v[20:21], v[4:7], off
	s_cbranch_scc0 .LBB0_782
	s_add_i32 s20, s20, s84
	v_add_u32_e32 v120, s3, v120
	v_add_u32_e32 v121, s3, v121
	v_add_u32_e32 v122, s3, v122
	v_add_u32_e32 v123, s3, v123
	s_cmpk_gt_i32 s20, 0x427
	v_add_u32_e32 v168, s3, v168
	s_barrier
	s_cmp_eq_u32 s84, 0x200
	s_cbranch_scc0 .Lp5_orig
	s_cmp_lt_u32 s2, 40
	s_cbranch_scc1 .Lp5_lo
	s_cmp_lt_u32 s2, 80
	s_cbranch_scc0 .Lp5_orig
	s_add_i32 s6, s2, 0x400
	s_cmp_eq_u32 s20, s6
	s_cbranch_scc0 .Lp5_orig
	s_sub_i32 s20, s20, 40
	v_add_u32_e32 v120, 0xffffec00, v120
	v_add_u32_e32 v121, 0xffffec00, v121
	v_add_u32_e32 v122, 0xffffec00, v122
	v_add_u32_e32 v123, 0xffffec00, v123
	v_add_u32_e32 v168, 0xffffec00, v168
	s_branch .LBB0_773
.Lp5_lo:
	s_cmpk_gt_i32 s20, 0x3ff
	s_cbranch_scc1 .LBB0_784
.Lp5_orig:
	s_cmpk_gt_i32 s20, 0x427
	s_cbranch_scc0 .LBB0_773
